# layer-1 weight conversion moved into the idle tails of the 1408-tile FFN-in GEMMs (WGs 128..255), removed from layer-1 top
# speedup vs baseline: 1.0017x; 1.0017x over previous
.LBB0_57:
.LBB0_78:
	s_mul_i32 s4, s31, 0x48000
	s_add_u32 s70, s28, s4
	s_addc_u32 s71, s29, 0
	s_and_b64 s[4:5], s[0:1], exec
	v_readlane_b32 s4, v249, 33
	v_readlane_b32 s6, v249, 35
	v_mov_b32_e32 v0, v179
	v_readlane_b32 s5, v249, 34
	v_readlane_b32 s7, v249, 36
	s_cselect_b32 s6, s4, s26
	v_readlane_b32 s10, v249, 39
	v_readfirstlane_b32 s4, v0
	s_cselect_b32 s7, s5, s27
	s_ashr_i32 s4, s4, 6
	v_readlane_b32 s5, v249, 24
	s_lshl_b32 s94, s31, 10
	s_add_i32 s10, s4, s5
	s_cmpk_gt_i32 s10, 0x7ff
	s_mov_b32 s95, s45
	v_readlane_b32 s8, v249, 37
	v_readlane_b32 s9, v249, 38
	v_readlane_b32 s11, v249, 40
	v_readlane_b32 s12, v249, 41
	v_readlane_b32 s13, v249, 42
	v_readlane_b32 s14, v249, 43
	v_readlane_b32 s15, v249, 44
	v_readlane_b32 s16, v249, 45
	v_readlane_b32 s17, v249, 46
	v_readlane_b32 s18, v249, 47
	v_readlane_b32 s19, v249, 48
	s_cbranch_scc1 .LBB0_84
	v_readlane_b32 s48, v249, 33
	s_lshl_b64 s[8:9], s[94:95], 2
	v_readlane_b32 s52, v249, 37
	v_readlane_b32 s53, v249, 38
	s_add_u32 s8, s52, s8
	v_lshlrev_b32_e32 v1, 4, v0
	s_addc_u32 s9, s53, s9
	v_and_b32_e32 v156, 0x3f0, v1
	v_and_b32_e32 v0, 63, v0
	v_lshl_add_u64 v[16:17], s[8:9], 0, v[156:157]
	v_lshl_add_u64 v[18:19], s[70:71], 0, v[156:157]
	v_lshlrev_b32_e32 v156, 3, v0
	v_lshl_add_u64 v[22:23], s[28:29], 0, v[156:157]
	v_lshlrev_b32_e32 v156, 4, v0
	s_lshl_b32 s4, s4, 3
	v_readlane_b32 s5, v251, 25
	v_lshl_add_u64 v[0:1], s[6:7], 0, v[156:157]
	s_mov_b64 s[8:9], 0xc00
	v_lshl_add_u64 v[20:21], v[18:19], 0, s[66:67]
	s_add_i32 s4, s5, s4
	v_lshl_add_u64 v[24:25], v[0:1], 0, s[8:9]
	v_readlane_b32 s14, v252, 52
	v_readlane_b32 s49, v249, 34
	v_readlane_b32 s50, v249, 35
	v_readlane_b32 s51, v249, 36
	v_readlane_b32 s54, v249, 39
	v_readlane_b32 s55, v249, 40
	v_readlane_b32 s56, v249, 41
	v_readlane_b32 s57, v249, 42
	v_readlane_b32 s58, v249, 43
	v_readlane_b32 s59, v249, 44
	v_readlane_b32 s60, v249, 45
	v_readlane_b32 s61, v249, 46
	v_readlane_b32 s62, v249, 47
	v_readlane_b32 s63, v249, 48

.LBB0_151:
	s_waitcnt vmcnt(0)
	v_readlane_b32 s22, v249, 25
	v_readlane_b32 s50, v253, 21
	v_readlane_b32 s48, v253, 23
	v_readlane_b32 s52, v253, 25
	v_readlane_b32 s23, v249, 26
	v_readlane_b32 s51, v253, 22
	v_readlane_b32 s49, v253, 24
	v_readlane_b32 s53, v253, 26
	s_barrier
	v_readlane_b32 s100, v253, 28
	v_readlane_b32 s101, v249, 24
	s_cmp_eq_u32 s100, 0
	s_cbranch_scc1 .Lcvb_skip
	s_cmpk_lt_u32 s101, 0x400
	s_cbranch_scc1 .Lcvb_skip
	v_writelane_b32 v242, s0, 0
	v_writelane_b32 v242, s1, 1
	v_writelane_b32 v242, s2, 2
	v_writelane_b32 v242, s3, 3
	v_writelane_b32 v242, s4, 4
	v_writelane_b32 v242, s5, 5
	v_writelane_b32 v242, s6, 6
	v_writelane_b32 v242, s7, 7
	v_writelane_b32 v242, s8, 8
	v_writelane_b32 v242, s9, 9
	v_writelane_b32 v242, s10, 10
	v_writelane_b32 v242, s11, 11
	v_writelane_b32 v242, s12, 12
	v_writelane_b32 v242, s13, 13
	v_writelane_b32 v242, s14, 14
	v_writelane_b32 v242, s15, 15
	v_writelane_b32 v242, s16, 16
	v_writelane_b32 v242, s17, 17
	v_writelane_b32 v242, s18, 18
	v_writelane_b32 v242, s19, 19
	v_writelane_b32 v242, s20, 20
	v_writelane_b32 v242, s21, 21
	v_writelane_b32 v242, s22, 22
	v_writelane_b32 v242, s23, 23
	v_writelane_b32 v242, s24, 24
	v_writelane_b32 v242, s25, 25
	v_writelane_b32 v242, s26, 26
	v_writelane_b32 v242, s27, 27
	v_writelane_b32 v242, s28, 28
	v_writelane_b32 v242, s29, 29
	v_writelane_b32 v242, s30, 30
	v_writelane_b32 v242, s31, 31
	v_writelane_b32 v242, s32, 32
	v_writelane_b32 v242, s33, 33
	v_writelane_b32 v242, s34, 34
	v_writelane_b32 v242, s35, 35
	v_writelane_b32 v242, s36, 36
	v_writelane_b32 v242, s37, 37
	v_writelane_b32 v242, s38, 38
	v_writelane_b32 v242, s39, 39
	v_writelane_b32 v242, s40, 40
	v_writelane_b32 v242, s41, 41
	v_writelane_b32 v242, s42, 42
	v_writelane_b32 v242, s43, 43
	v_writelane_b32 v242, s44, 44
	v_writelane_b32 v242, s45, 45
	v_writelane_b32 v242, s46, 46
	v_writelane_b32 v242, s47, 47
	v_writelane_b32 v242, s48, 48
	v_writelane_b32 v242, s49, 49
	v_writelane_b32 v242, s50, 50
	v_writelane_b32 v242, s51, 51
	v_writelane_b32 v242, s52, 52
	v_writelane_b32 v242, s53, 53
	v_writelane_b32 v242, s54, 54
	v_writelane_b32 v242, s55, 55
	v_writelane_b32 v242, s56, 56
	v_writelane_b32 v242, s57, 57
	v_writelane_b32 v242, s58, 58
	v_writelane_b32 v242, s59, 59
	v_writelane_b32 v242, s60, 60
	v_writelane_b32 v242, s61, 61
	v_writelane_b32 v242, s62, 62
	v_writelane_b32 v242, s63, 63
	v_writelane_b32 v243, s64, 0
	v_writelane_b32 v243, s65, 1
	v_writelane_b32 v243, s66, 2
	v_writelane_b32 v243, s67, 3
	v_writelane_b32 v243, s68, 4
	v_writelane_b32 v243, s69, 5
	v_writelane_b32 v243, s70, 6
	v_writelane_b32 v243, s71, 7
	v_writelane_b32 v243, s72, 8
	v_writelane_b32 v243, s73, 9
	v_writelane_b32 v243, s74, 10
	v_writelane_b32 v243, s75, 11
	v_writelane_b32 v243, s76, 12
	v_writelane_b32 v243, s77, 13
	v_writelane_b32 v243, s78, 14
	v_writelane_b32 v243, s79, 15
	v_writelane_b32 v243, s80, 16
	v_writelane_b32 v243, s81, 17
	v_writelane_b32 v243, s82, 18
	v_writelane_b32 v243, s83, 19
	v_writelane_b32 v243, s84, 20
	v_writelane_b32 v243, s85, 21
	v_writelane_b32 v243, s86, 22
	v_writelane_b32 v243, s87, 23
	v_writelane_b32 v243, s88, 24
	v_writelane_b32 v243, s89, 25
	v_writelane_b32 v243, s90, 26
	v_writelane_b32 v243, s91, 27
	v_writelane_b32 v243, s92, 28
	v_writelane_b32 v243, s93, 29
	v_writelane_b32 v243, s94, 30
	v_writelane_b32 v243, s95, 31
	v_writelane_b32 v243, s96, 32
	v_writelane_b32 v243, s97, 33
	v_writelane_b32 v243, s98, 34
	v_writelane_b32 v243, s99, 35
	v_writelane_b32 v243, vcc_lo, 38
	v_writelane_b32 v243, vcc_hi, 39
	v_readlane_b32 s60, v253, 17
	v_readlane_b32 s61, v253, 18
	s_movk_i32 s100, 0x1a00
	s_movk_i32 s101, 0x2a80
	v_mov_b32_e32 v0, v179
	v_readlane_b32 s5, v249, 24
	v_readfirstlane_b32 s4, v0
	s_ashr_i32 s4, s4, 6
	s_add_i32 s8, s4, s5
	v_bfe_u32 v18, v0, 5, 1
	v_and_b32_e32 v16, 31, v0
	v_bfe_u32 v20, v0, 3, 3
	v_lshlrev_b32_e32 v0, 3, v0
	s_lshl_b32 s5, s4, 14
	v_and_b32_e32 v26, 56, v0
	v_readlane_b32 s6, v252, 39
	s_add_i32 s5, s5, 0
	v_lshlrev_b32_e32 v14, 2, v16
	v_mul_u32_u24_e32 v1, 0x84, v18
	v_lshlrev_b32_e32 v156, 1, v26
	v_readlane_b32 s7, v252, 40
	v_add3_u32 v19, s5, v14, v1
	v_mov_b32_e32 v15, v157
	v_lshl_add_u64 v[0:1], s[6:7], 0, v[156:157]
	v_readlane_b32 s6, v252, 7
	v_readlane_b32 s7, v252, 8
	v_mul_u32_u24_e32 v2, 0x84, v26
	v_lshlrev_b32_e32 v3, 2, v20
	v_lshl_add_u64 v[4:5], s[6:7], 0, v[156:157]
	v_readlane_b32 s6, v251, 56
	v_readlane_b32 s7, v251, 57
	v_add3_u32 v21, s5, v2, v3
	s_lshl_b32 s5, s4, 1
	v_lshl_add_u64 v[6:7], s[6:7], 0, v[156:157]
	v_readlane_b32 s6, v249, 27
	v_readlane_b32 s7, v249, 28
	s_lshl_b32 s4, s4, 5
	s_mov_b64 s[70:71], s[22:23]
	v_lshl_add_u64 v[8:9], s[6:7], 0, v[14:15]
	v_readlane_b32 s6, v249, 29
	v_readlane_b32 s7, v249, 30
	v_or_b32_e32 v22, 8, v20
	v_or_b32_e32 v23, 16, v20
	v_lshl_add_u64 v[10:11], s[6:7], 0, v[14:15]
	v_readlane_b32 s6, v249, 31
	v_readlane_b32 s7, v249, 32
	v_or_b32_e32 v24, 24, v20
	v_lshl_add_u64 v[2:3], s[60:61], 0, v[156:157]
	v_lshl_add_u64 v[12:13], s[6:7], 0, v[14:15]
	v_readlane_b32 s6, v249, 49
	v_readlane_b32 s7, v249, 50
	v_lshlrev_b32_e32 v156, 2, v16
	v_lshlrev_b32_e32 v16, 1, v26
	v_lshl_add_u64 v[14:15], s[6:7], 0, v[14:15]
	v_readlane_b32 s6, v252, 49
	s_add_i32 s9, s6, s5
	v_readlane_b32 s5, v251, 18
	s_add_i32 s10, s5, s4
	v_add_u32_e32 v25, 0x400, v19
	v_add_u32_e32 v26, 0x800, v19
	v_add_u32_e32 v27, 0xc00, v19
	v_add_u32_e32 v28, 0x1000, v19
	v_add_u32_e32 v29, 0x1400, v19
	v_add_u32_e32 v30, 0x1800, v19
	v_add_u32_e32 v31, 0x1c00, v19
	s_movk_i32 s16, 0x7000
	s_mov_b32 s17, 0xf000
	s_mov_b32 s18, 0x16000
	s_mov_b32 s19, 0x25000
	s_mov_b32 s22, 0x2d000
	s_mov_b32 s23, 0x34000
	s_mov_b32 s40, 0x3c000
	s_mov_b32 s41, 0x43000
	s_mov_b32 s46, 0x4b000
	s_mov_b32 s47, 0x52000
	s_mov_b32 s56, 0x5a000
	s_mov_b32 s57, 0x61000
	s_mov_b32 s58, 0x69000
	s_mov_b32 s59, 0x70000
	s_addk_i32 s8, 0xfc00
	s_add_i32 s8, s8, s100
	s_lshl_b32 s9, s8, 1
	s_add_i32 s9, s9, 0x7fffd000
	s_lshl_b32 s10, s8, 5
	s_cmp_lt_i32 s8, s101
	s_cbranch_scc0 .Lcvb_77
	s_branch .Lcvb_61
.Lcvb_60:
	s_addk_i32 s8, 0x400
	s_addk_i32 s9, 0x800
	s_add_i32 s10, s10, 0x8000
	s_cmp_lt_i32 s8, s101
	s_cbranch_scc0 .Lcvb_77

.Lcvb_77:
	v_readlane_b32 s0, v242, 0
	v_readlane_b32 s1, v242, 1
	v_readlane_b32 s2, v242, 2
	v_readlane_b32 s3, v242, 3
	v_readlane_b32 s4, v242, 4
	v_readlane_b32 s5, v242, 5
	v_readlane_b32 s6, v242, 6
	v_readlane_b32 s7, v242, 7
	v_readlane_b32 s8, v242, 8
	v_readlane_b32 s9, v242, 9
	v_readlane_b32 s10, v242, 10
	v_readlane_b32 s11, v242, 11
	v_readlane_b32 s12, v242, 12
	v_readlane_b32 s13, v242, 13
	v_readlane_b32 s14, v242, 14
	v_readlane_b32 s15, v242, 15
	v_readlane_b32 s16, v242, 16
	v_readlane_b32 s17, v242, 17
	v_readlane_b32 s18, v242, 18
	v_readlane_b32 s19, v242, 19
	v_readlane_b32 s20, v242, 20
	v_readlane_b32 s21, v242, 21
	v_readlane_b32 s22, v242, 22
	v_readlane_b32 s23, v242, 23
	v_readlane_b32 s24, v242, 24
	v_readlane_b32 s25, v242, 25
	v_readlane_b32 s26, v242, 26
	v_readlane_b32 s27, v242, 27
	v_readlane_b32 s28, v242, 28
	v_readlane_b32 s29, v242, 29
	v_readlane_b32 s30, v242, 30
	v_readlane_b32 s31, v242, 31
	v_readlane_b32 s32, v242, 32
	v_readlane_b32 s33, v242, 33
	v_readlane_b32 s34, v242, 34
	v_readlane_b32 s35, v242, 35
	v_readlane_b32 s36, v242, 36
	v_readlane_b32 s37, v242, 37
	v_readlane_b32 s38, v242, 38
	v_readlane_b32 s39, v242, 39
	v_readlane_b32 s40, v242, 40
	v_readlane_b32 s41, v242, 41
	v_readlane_b32 s42, v242, 42
	v_readlane_b32 s43, v242, 43
	v_readlane_b32 s44, v242, 44
	v_readlane_b32 s45, v242, 45
	v_readlane_b32 s46, v242, 46
	v_readlane_b32 s47, v242, 47
	v_readlane_b32 s48, v242, 48
	v_readlane_b32 s49, v242, 49
	v_readlane_b32 s50, v242, 50
	v_readlane_b32 s51, v242, 51
	v_readlane_b32 s52, v242, 52
	v_readlane_b32 s53, v242, 53
	v_readlane_b32 s54, v242, 54
	v_readlane_b32 s55, v242, 55
	v_readlane_b32 s56, v242, 56
	v_readlane_b32 s57, v242, 57
	v_readlane_b32 s58, v242, 58
	v_readlane_b32 s59, v242, 59
	v_readlane_b32 s60, v242, 60
	v_readlane_b32 s61, v242, 61
	v_readlane_b32 s62, v242, 62
	v_readlane_b32 s63, v242, 63
	v_readlane_b32 s64, v243, 0
	v_readlane_b32 s65, v243, 1
	v_readlane_b32 s66, v243, 2
	v_readlane_b32 s67, v243, 3
	v_readlane_b32 s68, v243, 4
	v_readlane_b32 s69, v243, 5
	v_readlane_b32 s70, v243, 6
	v_readlane_b32 s71, v243, 7
	v_readlane_b32 s72, v243, 8
	v_readlane_b32 s73, v243, 9
	v_readlane_b32 s74, v243, 10
	v_readlane_b32 s75, v243, 11
	v_readlane_b32 s76, v243, 12
	v_readlane_b32 s77, v243, 13
	v_readlane_b32 s78, v243, 14
	v_readlane_b32 s79, v243, 15
	v_readlane_b32 s80, v243, 16
	v_readlane_b32 s81, v243, 17
	v_readlane_b32 s82, v243, 18
	v_readlane_b32 s83, v243, 19
	v_readlane_b32 s84, v243, 20
	v_readlane_b32 s85, v243, 21
	v_readlane_b32 s86, v243, 22
	v_readlane_b32 s87, v243, 23
	v_readlane_b32 s88, v243, 24
	v_readlane_b32 s89, v243, 25
	v_readlane_b32 s90, v243, 26
	v_readlane_b32 s91, v243, 27
	v_readlane_b32 s92, v243, 28
	v_readlane_b32 s93, v243, 29
	v_readlane_b32 s94, v243, 30
	v_readlane_b32 s95, v243, 31
	v_readlane_b32 s96, v243, 32
	v_readlane_b32 s97, v243, 33
	v_readlane_b32 s98, v243, 34
	v_readlane_b32 s99, v243, 35
	v_readlane_b32 vcc_lo, v243, 38
	v_readlane_b32 vcc_hi, v243, 39
.Lcvb_skip:
.LBB0_152:
	s_waitcnt vmcnt(0)
	s_waitcnt vmcnt(0)
	s_barrier
	s_and_saveexec_b64 s[0:1], s[22:23]
	s_movk_i32 s60, 0x79
	v_readlane_b32 s61, v252, 54
	s_cbranch_execz .LBB0_204
	v_readlane_b32 s4, v253, 7
	s_waitcnt vmcnt(0) expcnt(0) lgkmcnt(0)
	s_nop 0
	v_mov_b32_e32 v0, s4
	ds_read_b32 v2, v0
	v_readlane_b32 s4, v253, 8
	s_waitcnt lgkmcnt(0)
	v_cmp_ne_u32_e32 vcc, 0, v2
	v_mov_b32_e32 v0, s4
	ds_read_b32 v0, v0
	s_cbranch_vccnz .LBB0_168
	s_mov_b32 s12, 1
	s_branch .LBB0_156

.LBB0_1102:
	s_waitcnt vmcnt(0)
	v_readlane_b32 s22, v249, 25
	v_readlane_b32 s50, v253, 21
	v_readlane_b32 s48, v253, 23
	v_readlane_b32 s52, v253, 25
	v_readlane_b32 s23, v249, 26
	v_readlane_b32 s51, v253, 22
	v_readlane_b32 s49, v253, 24
	v_readlane_b32 s53, v253, 26
	s_barrier
	v_readlane_b32 s100, v253, 28
	v_readlane_b32 s101, v249, 24
	s_cmp_lg_u32 s100, 0
	s_cbranch_scc1 .Lcva_skip
	s_cmpk_lt_u32 s101, 0x400
	s_cbranch_scc1 .Lcva_skip
	v_writelane_b32 v242, s0, 0
	v_writelane_b32 v242, s1, 1
	v_writelane_b32 v242, s2, 2
	v_writelane_b32 v242, s3, 3
	v_writelane_b32 v242, s4, 4
	v_writelane_b32 v242, s5, 5
	v_writelane_b32 v242, s6, 6
	v_writelane_b32 v242, s7, 7
	v_writelane_b32 v242, s8, 8
	v_writelane_b32 v242, s9, 9
	v_writelane_b32 v242, s10, 10
	v_writelane_b32 v242, s11, 11
	v_writelane_b32 v242, s12, 12
	v_writelane_b32 v242, s13, 13
	v_writelane_b32 v242, s14, 14
	v_writelane_b32 v242, s15, 15
	v_writelane_b32 v242, s16, 16
	v_writelane_b32 v242, s17, 17
	v_writelane_b32 v242, s18, 18
	v_writelane_b32 v242, s19, 19
	v_writelane_b32 v242, s20, 20
	v_writelane_b32 v242, s21, 21
	v_writelane_b32 v242, s22, 22
	v_writelane_b32 v242, s23, 23
	v_writelane_b32 v242, s24, 24
	v_writelane_b32 v242, s25, 25
	v_writelane_b32 v242, s26, 26
	v_writelane_b32 v242, s27, 27
	v_writelane_b32 v242, s28, 28
	v_writelane_b32 v242, s29, 29
	v_writelane_b32 v242, s30, 30
	v_writelane_b32 v242, s31, 31
	v_writelane_b32 v242, s32, 32
	v_writelane_b32 v242, s33, 33
	v_writelane_b32 v242, s34, 34
	v_writelane_b32 v242, s35, 35
	v_writelane_b32 v242, s36, 36
	v_writelane_b32 v242, s37, 37
	v_writelane_b32 v242, s38, 38
	v_writelane_b32 v242, s39, 39
	v_writelane_b32 v242, s40, 40
	v_writelane_b32 v242, s41, 41
	v_writelane_b32 v242, s42, 42
	v_writelane_b32 v242, s43, 43
	v_writelane_b32 v242, s44, 44
	v_writelane_b32 v242, s45, 45
	v_writelane_b32 v242, s46, 46
	v_writelane_b32 v242, s47, 47
	v_writelane_b32 v242, s48, 48
	v_writelane_b32 v242, s49, 49
	v_writelane_b32 v242, s50, 50
	v_writelane_b32 v242, s51, 51
	v_writelane_b32 v242, s52, 52
	v_writelane_b32 v242, s53, 53
	v_writelane_b32 v242, s54, 54
	v_writelane_b32 v242, s55, 55
	v_writelane_b32 v242, s56, 56
	v_writelane_b32 v242, s57, 57
	v_writelane_b32 v242, s58, 58
	v_writelane_b32 v242, s59, 59
	v_writelane_b32 v242, s60, 60
	v_writelane_b32 v242, s61, 61
	v_writelane_b32 v242, s62, 62
	v_writelane_b32 v242, s63, 63
	v_writelane_b32 v243, s64, 0
	v_writelane_b32 v243, s65, 1
	v_writelane_b32 v243, s66, 2
	v_writelane_b32 v243, s67, 3
	v_writelane_b32 v243, s68, 4
	v_writelane_b32 v243, s69, 5
	v_writelane_b32 v243, s70, 6
	v_writelane_b32 v243, s71, 7
	v_writelane_b32 v243, s72, 8
	v_writelane_b32 v243, s73, 9
	v_writelane_b32 v243, s74, 10
	v_writelane_b32 v243, s75, 11
	v_writelane_b32 v243, s76, 12
	v_writelane_b32 v243, s77, 13
	v_writelane_b32 v243, s78, 14
	v_writelane_b32 v243, s79, 15
	v_writelane_b32 v243, s80, 16
	v_writelane_b32 v243, s81, 17
	v_writelane_b32 v243, s82, 18
	v_writelane_b32 v243, s83, 19
	v_writelane_b32 v243, s84, 20
	v_writelane_b32 v243, s85, 21
	v_writelane_b32 v243, s86, 22
	v_writelane_b32 v243, s87, 23
	v_writelane_b32 v243, s88, 24
	v_writelane_b32 v243, s89, 25
	v_writelane_b32 v243, s90, 26
	v_writelane_b32 v243, s91, 27
	v_writelane_b32 v243, s92, 28
	v_writelane_b32 v243, s93, 29
	v_writelane_b32 v243, s94, 30
	v_writelane_b32 v243, s95, 31
	v_writelane_b32 v243, s96, 32
	v_writelane_b32 v243, s97, 33
	v_writelane_b32 v243, s98, 34
	v_writelane_b32 v243, s99, 35
	v_writelane_b32 v243, vcc_lo, 38
	v_writelane_b32 v243, vcc_hi, 39
	v_readlane_b32 s60, v253, 17
	v_readlane_b32 s61, v253, 18
	s_mov_b32 s100, 0
	s_movk_i32 s101, 0x1a00
	v_mov_b32_e32 v0, v179
	v_readlane_b32 s5, v249, 24
	v_readfirstlane_b32 s4, v0
	s_ashr_i32 s4, s4, 6
	s_add_i32 s8, s4, s5
	v_bfe_u32 v18, v0, 5, 1
	v_and_b32_e32 v16, 31, v0
	v_bfe_u32 v20, v0, 3, 3
	v_lshlrev_b32_e32 v0, 3, v0
	s_lshl_b32 s5, s4, 14
	v_and_b32_e32 v26, 56, v0
	v_readlane_b32 s6, v252, 39
	s_add_i32 s5, s5, 0
	v_lshlrev_b32_e32 v14, 2, v16
	v_mul_u32_u24_e32 v1, 0x84, v18
	v_lshlrev_b32_e32 v156, 1, v26
	v_readlane_b32 s7, v252, 40
	v_add3_u32 v19, s5, v14, v1
	v_mov_b32_e32 v15, v157
	v_lshl_add_u64 v[0:1], s[6:7], 0, v[156:157]
	v_readlane_b32 s6, v252, 7
	v_readlane_b32 s7, v252, 8
	v_mul_u32_u24_e32 v2, 0x84, v26
	v_lshlrev_b32_e32 v3, 2, v20
	v_lshl_add_u64 v[4:5], s[6:7], 0, v[156:157]
	v_readlane_b32 s6, v251, 56
	v_readlane_b32 s7, v251, 57
	v_add3_u32 v21, s5, v2, v3
	s_lshl_b32 s5, s4, 1
	v_lshl_add_u64 v[6:7], s[6:7], 0, v[156:157]
	v_readlane_b32 s6, v249, 27
	v_readlane_b32 s7, v249, 28
	s_lshl_b32 s4, s4, 5
	s_mov_b64 s[70:71], s[22:23]
	v_lshl_add_u64 v[8:9], s[6:7], 0, v[14:15]
	v_readlane_b32 s6, v249, 29
	v_readlane_b32 s7, v249, 30
	v_or_b32_e32 v22, 8, v20
	v_or_b32_e32 v23, 16, v20
	v_lshl_add_u64 v[10:11], s[6:7], 0, v[14:15]
	v_readlane_b32 s6, v249, 31
	v_readlane_b32 s7, v249, 32
	v_or_b32_e32 v24, 24, v20
	v_lshl_add_u64 v[2:3], s[60:61], 0, v[156:157]
	v_lshl_add_u64 v[12:13], s[6:7], 0, v[14:15]
	v_readlane_b32 s6, v249, 49
	v_readlane_b32 s7, v249, 50
	v_lshlrev_b32_e32 v156, 2, v16
	v_lshlrev_b32_e32 v16, 1, v26
	v_lshl_add_u64 v[14:15], s[6:7], 0, v[14:15]
	v_readlane_b32 s6, v252, 49
	s_add_i32 s9, s6, s5
	v_readlane_b32 s5, v251, 18
	s_add_i32 s10, s5, s4
	v_add_u32_e32 v25, 0x400, v19
	v_add_u32_e32 v26, 0x800, v19
	v_add_u32_e32 v27, 0xc00, v19
	v_add_u32_e32 v28, 0x1000, v19
	v_add_u32_e32 v29, 0x1400, v19
	v_add_u32_e32 v30, 0x1800, v19
	v_add_u32_e32 v31, 0x1c00, v19
	s_movk_i32 s16, 0x7000
	s_mov_b32 s17, 0xf000
	s_mov_b32 s18, 0x16000
	s_mov_b32 s19, 0x25000
	s_mov_b32 s22, 0x2d000
	s_mov_b32 s23, 0x34000
	s_mov_b32 s40, 0x3c000
	s_mov_b32 s41, 0x43000
	s_mov_b32 s46, 0x4b000
	s_mov_b32 s47, 0x52000
	s_mov_b32 s56, 0x5a000
	s_mov_b32 s57, 0x61000
	s_mov_b32 s58, 0x69000
	s_mov_b32 s59, 0x70000
	s_addk_i32 s8, 0xfc00
	s_add_i32 s8, s8, s100
	s_lshl_b32 s9, s8, 1
	s_add_i32 s9, s9, 0x7fffd000
	s_lshl_b32 s10, s8, 5
	s_cmp_lt_i32 s8, s101
	s_cbranch_scc0 .Lcva_77
	s_branch .Lcva_61

.Lcva_skip:
.LBB0_1103:
	s_waitcnt vmcnt(0)
	s_waitcnt vmcnt(0)
	s_barrier
	s_and_saveexec_b64 s[0:1], s[22:23]
	s_cbranch_execz .LBB0_1155
	v_readlane_b32 s4, v253, 7
	s_waitcnt vmcnt(0) expcnt(0) lgkmcnt(0)
	s_nop 0
	v_mov_b32_e32 v0, s4
	ds_read_b32 v2, v0
	v_readlane_b32 s4, v253, 8
	s_waitcnt lgkmcnt(0)
	v_cmp_ne_u32_e32 vcc, 0, v2
	v_mov_b32_e32 v0, s4
	ds_read_b32 v0, v0
	s_cbranch_vccnz .LBB0_1119
	s_mov_b32 s10, 1
	s_branch .LBB0_1107
